# hook: original code kept as fallback for grids other than 256 workgroups (scalar guard); otherwise as previous version
# speedup vs baseline: 1.1879x; 1.0028x over previous
; #define lane lane_id()
; __device__ __forceinline__ void conv_load4(const float* __restrict__ W, int N, int item, int lane, f32x4 (&x)[16]) {
;     const int nblk = N / 64, k0 = 64 * (item / nblk), n0 = 64 * (item % nblk);
; #pragma unroll
;     for (int i = 0; i < 16; ++i) x[i] = __builtin_nontemporal_load((const f32x4*)(W + (size_t)(k0 + 4 * i + (lane >> 4)) * N + n0 + 4 * (lane & 15)));
; }
;     __device__ __forceinline__ void done(const Unit&) const {
;     ...
;         for (int it = gw; it < I3; it += 2 * ngw) {
;             const bool two = it + ngw < I3;
;             conv_load4(w3, 4 * DM, it, ln, va); if (two) conv_load4(w3, 4 * DM, it + ngw, ln, vb);
;             conv_xpose(va, ln); if (two) conv_xpose(vb, ln);
;             conv_store4_lds(DM, 4 * DM, t3, it, ln, g1, va, sw); if (two) conv_store4_lds(DM, 4 * DM, t3, it + ngw, ln, g1, vb, sw);
.LBB0_153:
	s_cmpk_lg_u32 s63, 0x1000
	s_cbranch_scc1 .Lhk_generic
	s_waitcnt lgkmcnt(0)
	v_add_u32_e32 v246, v198, v199
	v_add_u32_e32 v247, v198, v201
	s_waitcnt vmcnt(0)
	s_mov_b32 s37, s96
	s_lshr_b32 s18, s37, 7
	s_lshl_b32 s18, s18, 6
	s_and_b32 s19, s37, 127
	s_lshl_b32 s19, s19, 6
	s_lshl_b32 s49, s19, 12
	s_lshl_b32 s50, s18, 1
	s_add_i32 s24, s49, s50
	v_add_u32_e32 v240, s18, v153
	v_mov_b32_e32 v241, 0
	v_lshlrev_b64 v[240:241], 15, v[240:241]
	s_lshl_b32 s100, s19, 2
	s_mov_b32 s101, 0
	v_lshl_add_u64 v[238:239], s[100:101], 0, v[136:137]
	v_lshl_add_u64 v[238:239], v[238:239], 0, v[240:241]
	s_mov_b32 s46, 0x20000
	s_mov_b32 s47, 0
	global_load_dwordx4 v[0:3], v[238:239], off nt
	v_lshl_add_u64 v[238:239], v[238:239], 0, s[46:47]
	global_load_dwordx4 v[4:7], v[238:239], off nt
	v_lshl_add_u64 v[238:239], v[238:239], 0, s[46:47]
	global_load_dwordx4 v[8:11], v[238:239], off nt
	v_lshl_add_u64 v[238:239], v[238:239], 0, s[46:47]
	global_load_dwordx4 v[12:15], v[238:239], off nt
	v_lshl_add_u64 v[238:239], v[238:239], 0, s[46:47]
	global_load_dwordx4 v[16:19], v[238:239], off nt
	v_lshl_add_u64 v[238:239], v[238:239], 0, s[46:47]
	global_load_dwordx4 v[20:23], v[238:239], off nt
	v_lshl_add_u64 v[238:239], v[238:239], 0, s[46:47]
	global_load_dwordx4 v[24:27], v[238:239], off nt
	v_lshl_add_u64 v[238:239], v[238:239], 0, s[46:47]
	global_load_dwordx4 v[28:31], v[238:239], off nt
	v_lshl_add_u64 v[238:239], v[238:239], 0, s[46:47]
	global_load_dwordx4 v[32:35], v[238:239], off nt
	v_lshl_add_u64 v[238:239], v[238:239], 0, s[46:47]
	global_load_dwordx4 v[36:39], v[238:239], off nt
	v_lshl_add_u64 v[238:239], v[238:239], 0, s[46:47]
	global_load_dwordx4 v[40:43], v[238:239], off nt
	v_lshl_add_u64 v[238:239], v[238:239], 0, s[46:47]
	global_load_dwordx4 v[44:47], v[238:239], off nt
	v_lshl_add_u64 v[238:239], v[238:239], 0, s[46:47]
	global_load_dwordx4 v[48:51], v[238:239], off nt
	v_lshl_add_u64 v[238:239], v[238:239], 0, s[46:47]
	global_load_dwordx4 v[52:55], v[238:239], off nt
	v_lshl_add_u64 v[238:239], v[238:239], 0, s[46:47]
	global_load_dwordx4 v[56:59], v[238:239], off nt
	v_lshl_add_u64 v[238:239], v[238:239], 0, s[46:47]
	global_load_dwordx4 v[60:63], v[238:239], off nt
	s_lshl_b32 s50, s18, 2
	s_add_u32 s98, s57, s50
	s_addc_u32 s99, s58, 0
	v_lshlrev_b32_e32 v242, 2, v153
	global_load_dword v158, v242, s[98:99]
	global_load_dword v159, v242, s[98:99] offset:16
	global_load_dword v160, v242, s[98:99] offset:32
	global_load_dword v161, v242, s[98:99] offset:48
	global_load_dword v162, v242, s[98:99] offset:64
	global_load_dword v163, v242, s[98:99] offset:80
	global_load_dword v164, v242, s[98:99] offset:96
	global_load_dword v165, v242, s[98:99] offset:112
	global_load_dword v166, v242, s[98:99] offset:128
	global_load_dword v167, v242, s[98:99] offset:144
	global_load_dword v168, v242, s[98:99] offset:160
	global_load_dword v169, v242, s[98:99] offset:176
	global_load_dword v170, v242, s[98:99] offset:192
	global_load_dword v171, v242, s[98:99] offset:208
	global_load_dword v172, v242, s[98:99] offset:224
	global_load_dword v173, v242, s[98:99] offset:240
	s_add_i32 s37, s96, 0x800
	s_lshr_b32 s18, s37, 7
	s_lshl_b32 s18, s18, 6
	s_and_b32 s19, s37, 127
	s_lshl_b32 s19, s19, 6
	s_lshl_b32 s49, s19, 12
	s_lshl_b32 s50, s18, 1
	s_add_i32 s25, s49, s50
	v_add_u32_e32 v240, s18, v153
	v_mov_b32_e32 v241, 0
	v_lshlrev_b64 v[240:241], 15, v[240:241]
	s_lshl_b32 s100, s19, 2
	s_mov_b32 s101, 0
	v_lshl_add_u64 v[238:239], s[100:101], 0, v[136:137]
	v_lshl_add_u64 v[238:239], v[238:239], 0, v[240:241]
	s_mov_b32 s46, 0x20000
	s_mov_b32 s47, 0
	global_load_dwordx4 v[64:67], v[238:239], off nt
	v_lshl_add_u64 v[238:239], v[238:239], 0, s[46:47]
	global_load_dwordx4 v[68:71], v[238:239], off nt
	v_lshl_add_u64 v[238:239], v[238:239], 0, s[46:47]
	global_load_dwordx4 v[72:75], v[238:239], off nt
	v_lshl_add_u64 v[238:239], v[238:239], 0, s[46:47]
	global_load_dwordx4 v[76:79], v[238:239], off nt
	v_lshl_add_u64 v[238:239], v[238:239], 0, s[46:47]
	global_load_dwordx4 v[80:83], v[238:239], off nt
	v_lshl_add_u64 v[238:239], v[238:239], 0, s[46:47]
	global_load_dwordx4 v[84:87], v[238:239], off nt
	v_lshl_add_u64 v[238:239], v[238:239], 0, s[46:47]
	global_load_dwordx4 v[88:91], v[238:239], off nt
	v_lshl_add_u64 v[238:239], v[238:239], 0, s[46:47]
	global_load_dwordx4 v[92:95], v[238:239], off nt
	v_lshl_add_u64 v[238:239], v[238:239], 0, s[46:47]
	global_load_dwordx4 v[96:99], v[238:239], off nt
	v_lshl_add_u64 v[238:239], v[238:239], 0, s[46:47]
	global_load_dwordx4 v[100:103], v[238:239], off nt
	v_lshl_add_u64 v[238:239], v[238:239], 0, s[46:47]
	global_load_dwordx4 v[104:107], v[238:239], off nt
	v_lshl_add_u64 v[238:239], v[238:239], 0, s[46:47]
	global_load_dwordx4 v[108:111], v[238:239], off nt
	v_lshl_add_u64 v[238:239], v[238:239], 0, s[46:47]
	global_load_dwordx4 v[112:115], v[238:239], off nt
	v_lshl_add_u64 v[238:239], v[238:239], 0, s[46:47]
	global_load_dwordx4 v[116:119], v[238:239], off nt
	v_lshl_add_u64 v[238:239], v[238:239], 0, s[46:47]
	global_load_dwordx4 v[120:123], v[238:239], off nt
	v_lshl_add_u64 v[238:239], v[238:239], 0, s[46:47]
	global_load_dwordx4 v[124:127], v[238:239], off nt
	s_waitcnt vmcnt(16)
; #define lane lane_id()
; __device__ __forceinline__ void conv_xpose(f32x4 (&x)[16], int lane) {
;     const bool a = (lane >> 4) & 1, b = (lane >> 5) & 1;
; #pragma unroll
;     for (int i = 0; i < 16; ++i) {
;         f32x4 v = x[i];
;         {
;             const float s0 = a ? v[0] : v[1], s1 = a ? v[2] : v[3];
;             const float r0 = __shfl_xor(s0, 16), r1 = __shfl_xor(s1, 16);
;             if (a) { v[0] = r0; v[2] = r1; } else { v[1] = r0; v[3] = r1; }
;         }
;         {
;             const float s0 = b ? v[0] : v[2], s1 = b ? v[1] : v[3];
;             const float r0 = __shfl_xor(s0, 32), r1 = __shfl_xor(s1, 32);
;             if (b) { v[0] = r0; v[1] = r1; } else { v[2] = r0; v[3] = r1; }
;         }
;         x[i] = v;
;     }
; }
; __device__ __forceinline__ void conv_store4(int K, int N, bf16_t* __restrict__ WT, int item, int lane, const float* __restrict__ gk, const f32x4 (&x)[16]) {
;     const int nblk = N / 64, k0 = 64 * (item / nblk), n0 = 64 * (item % nblk);
;     const int n = n0 + 4 * (lane & 15) + (lane >> 4);
; #pragma unroll
;     for (int kc = 0; kc < 8; ++kc) {
;         float g[8];
; #pragma unroll
;         for (int j = 0; j < 8; ++j) g[j] = gk ? gk[k0 + 8 * kc + j] : 1.0f;
;         const f32x4 lo = x[2 * kc], hi = x[2 * kc + 1];
;         u32x4 o; o.x = cvt_pk_bf16(lo[0] * g[0], lo[1] * g[1]); o.y = cvt_pk_bf16(lo[2] * g[2], lo[3] * g[3]);
;         o.z = cvt_pk_bf16(hi[0] * g[4], hi[1] * g[5]); o.w = cvt_pk_bf16(hi[2] * g[6], hi[3] * g[7]);
;         *(u32x4*)(WT + (size_t)n * K + k0 + 8 * kc) = o;
;     }
; }
; __device__ __forceinline__ void conv_store4_lds(int K, int N, bf16_t* __restrict__ WT, int item, int lane, const float* __restrict__ gk, const f32x4 (&x)[16], PG8_LAS unsigned char* sw) {
;     const int nblk = N / 64, k0 = 64 * (item / nblk), n0 = 64 * (item % nblk);
;     const int nq = lane & 15, r = lane >> 4;
;     u32x4 o[8];
; #pragma unroll
;     for (int kc = 0; kc < 8; ++kc) {
;         float g[8];
; #pragma unroll
;         for (int j = 0; j < 8; ++j) g[j] = gk ? gk[k0 + 8 * kc + j] : 1.0f;
;         const f32x4 lo = x[2 * kc], hi = x[2 * kc + 1];
;         o[kc].x = cvt_pk_bf16(lo[0] * g[0], lo[1] * g[1]); o[kc].y = cvt_pk_bf16(lo[2] * g[2], lo[3] * g[3]);
;         o[kc].z = cvt_pk_bf16(hi[0] * g[4], hi[1] * g[5]); o[kc].w = cvt_pk_bf16(hi[2] * g[6], hi[3] * g[7]);
;     }
	s_lshl_b32 s50, s18, 2
	s_add_u32 s98, s57, s50
	s_addc_u32 s99, s58, 0
	v_lshlrev_b32_e32 v242, 2, v153
	global_load_dword v174, v242, s[98:99]
	global_load_dword v175, v242, s[98:99] offset:16
	global_load_dword v176, v242, s[98:99] offset:32
	global_load_dword v177, v242, s[98:99] offset:48
	global_load_dword v178, v242, s[98:99] offset:64
	global_load_dword v179, v242, s[98:99] offset:80
	global_load_dword v180, v242, s[98:99] offset:96
	global_load_dword v181, v242, s[98:99] offset:112
	global_load_dword v182, v242, s[98:99] offset:128
	global_load_dword v183, v242, s[98:99] offset:144
	global_load_dword v184, v242, s[98:99] offset:160
	global_load_dword v185, v242, s[98:99] offset:176
	global_load_dword v186, v242, s[98:99] offset:192
	global_load_dword v187, v242, s[98:99] offset:208
	global_load_dword v188, v242, s[98:99] offset:224
	global_load_dword v189, v242, s[98:99] offset:240
	v_pk_mul_f32 v[0:1], v[0:1], v[158:159] op_sel_hi:[1,0]
	v_pk_mul_f32 v[2:3], v[2:3], v[158:159] op_sel_hi:[1,0]
	v_pk_mul_f32 v[4:5], v[4:5], v[158:159] op_sel:[0,1] op_sel_hi:[1,1]
	v_pk_mul_f32 v[6:7], v[6:7], v[158:159] op_sel:[0,1] op_sel_hi:[1,1]
	v_pk_mul_f32 v[8:9], v[8:9], v[160:161] op_sel_hi:[1,0]
	v_pk_mul_f32 v[10:11], v[10:11], v[160:161] op_sel_hi:[1,0]
	v_pk_mul_f32 v[12:13], v[12:13], v[160:161] op_sel:[0,1] op_sel_hi:[1,1]
	v_pk_mul_f32 v[14:15], v[14:15], v[160:161] op_sel:[0,1] op_sel_hi:[1,1]
	v_pk_mul_f32 v[16:17], v[16:17], v[162:163] op_sel_hi:[1,0]
	v_pk_mul_f32 v[18:19], v[18:19], v[162:163] op_sel_hi:[1,0]
	v_pk_mul_f32 v[20:21], v[20:21], v[162:163] op_sel:[0,1] op_sel_hi:[1,1]
	v_pk_mul_f32 v[22:23], v[22:23], v[162:163] op_sel:[0,1] op_sel_hi:[1,1]
	v_pk_mul_f32 v[24:25], v[24:25], v[164:165] op_sel_hi:[1,0]
	v_pk_mul_f32 v[26:27], v[26:27], v[164:165] op_sel_hi:[1,0]
	v_pk_mul_f32 v[28:29], v[28:29], v[164:165] op_sel:[0,1] op_sel_hi:[1,1]
	v_pk_mul_f32 v[30:31], v[30:31], v[164:165] op_sel:[0,1] op_sel_hi:[1,1]
	v_pk_mul_f32 v[32:33], v[32:33], v[166:167] op_sel_hi:[1,0]
	v_pk_mul_f32 v[34:35], v[34:35], v[166:167] op_sel_hi:[1,0]
	v_pk_mul_f32 v[36:37], v[36:37], v[166:167] op_sel:[0,1] op_sel_hi:[1,1]
	v_pk_mul_f32 v[38:39], v[38:39], v[166:167] op_sel:[0,1] op_sel_hi:[1,1]
	v_pk_mul_f32 v[40:41], v[40:41], v[168:169] op_sel_hi:[1,0]
	v_pk_mul_f32 v[42:43], v[42:43], v[168:169] op_sel_hi:[1,0]
	v_pk_mul_f32 v[44:45], v[44:45], v[168:169] op_sel:[0,1] op_sel_hi:[1,1]
	v_pk_mul_f32 v[46:47], v[46:47], v[168:169] op_sel:[0,1] op_sel_hi:[1,1]
	v_pk_mul_f32 v[48:49], v[48:49], v[170:171] op_sel_hi:[1,0]
	v_pk_mul_f32 v[50:51], v[50:51], v[170:171] op_sel_hi:[1,0]
	v_pk_mul_f32 v[52:53], v[52:53], v[170:171] op_sel:[0,1] op_sel_hi:[1,1]
	v_pk_mul_f32 v[54:55], v[54:55], v[170:171] op_sel:[0,1] op_sel_hi:[1,1]
	v_pk_mul_f32 v[56:57], v[56:57], v[172:173] op_sel_hi:[1,0]
	v_pk_mul_f32 v[58:59], v[58:59], v[172:173] op_sel_hi:[1,0]
	v_pk_mul_f32 v[60:61], v[60:61], v[172:173] op_sel:[0,1] op_sel_hi:[1,1]
	v_pk_mul_f32 v[62:63], v[62:63], v[172:173] op_sel:[0,1] op_sel_hi:[1,1]
	v_permlane16_swap_b32_e32 v0, v1
	v_permlane16_swap_b32_e32 v2, v3
	v_permlane16_swap_b32_e32 v4, v5
	v_permlane16_swap_b32_e32 v6, v7
	v_permlane16_swap_b32_e32 v8, v9
	v_permlane16_swap_b32_e32 v10, v11
	v_permlane16_swap_b32_e32 v12, v13
	v_permlane16_swap_b32_e32 v14, v15
	v_permlane16_swap_b32_e32 v16, v17
	v_permlane16_swap_b32_e32 v18, v19
	v_permlane16_swap_b32_e32 v20, v21
	v_permlane16_swap_b32_e32 v22, v23
	v_permlane16_swap_b32_e32 v24, v25
	v_permlane16_swap_b32_e32 v26, v27
	v_permlane16_swap_b32_e32 v28, v29
	v_permlane16_swap_b32_e32 v30, v31
	v_permlane16_swap_b32_e32 v32, v33
	v_permlane16_swap_b32_e32 v34, v35
	v_permlane16_swap_b32_e32 v36, v37
	v_permlane16_swap_b32_e32 v38, v39
	v_permlane16_swap_b32_e32 v40, v41
	v_permlane16_swap_b32_e32 v42, v43
	v_permlane16_swap_b32_e32 v44, v45
	v_permlane16_swap_b32_e32 v46, v47
	v_permlane16_swap_b32_e32 v48, v49
	v_permlane16_swap_b32_e32 v50, v51
	v_permlane16_swap_b32_e32 v52, v53
	v_permlane16_swap_b32_e32 v54, v55
	v_permlane16_swap_b32_e32 v56, v57
	v_permlane16_swap_b32_e32 v58, v59
	v_permlane16_swap_b32_e32 v60, v61
	v_permlane16_swap_b32_e32 v62, v63
	v_permlane32_swap_b32_e32 v0, v2
	v_permlane32_swap_b32_e32 v1, v3
	v_permlane32_swap_b32_e32 v4, v6
	v_permlane32_swap_b32_e32 v5, v7
	v_permlane32_swap_b32_e32 v8, v10
	v_permlane32_swap_b32_e32 v9, v11
	v_permlane32_swap_b32_e32 v12, v14
	v_permlane32_swap_b32_e32 v13, v15
	v_permlane32_swap_b32_e32 v16, v18
	v_permlane32_swap_b32_e32 v17, v19
	v_permlane32_swap_b32_e32 v20, v22
	v_permlane32_swap_b32_e32 v21, v23
	v_permlane32_swap_b32_e32 v24, v26
	v_permlane32_swap_b32_e32 v25, v27
	v_permlane32_swap_b32_e32 v28, v30
	v_permlane32_swap_b32_e32 v29, v31
	v_permlane32_swap_b32_e32 v32, v34
	v_permlane32_swap_b32_e32 v33, v35
	v_permlane32_swap_b32_e32 v36, v38
	v_permlane32_swap_b32_e32 v37, v39
	v_permlane32_swap_b32_e32 v40, v42
	v_permlane32_swap_b32_e32 v41, v43
	v_permlane32_swap_b32_e32 v44, v46
	v_permlane32_swap_b32_e32 v45, v47
	v_permlane32_swap_b32_e32 v48, v50
	v_permlane32_swap_b32_e32 v49, v51
	v_permlane32_swap_b32_e32 v52, v54
	v_permlane32_swap_b32_e32 v53, v55
	v_permlane32_swap_b32_e32 v56, v58
	v_permlane32_swap_b32_e32 v57, v59
	v_permlane32_swap_b32_e32 v60, v62
	v_permlane32_swap_b32_e32 v61, v63
	v_cvt_pk_bf16_f32 v206, v0, v1
	v_cvt_pk_bf16_f32 v207, v2, v3
	v_cvt_pk_bf16_f32 v208, v4, v5
	v_cvt_pk_bf16_f32 v209, v6, v7
	v_cvt_pk_bf16_f32 v210, v8, v9
	v_cvt_pk_bf16_f32 v211, v10, v11
	v_cvt_pk_bf16_f32 v212, v12, v13
	v_cvt_pk_bf16_f32 v213, v14, v15
	v_cvt_pk_bf16_f32 v214, v16, v17
; #define PG8_LAS __attribute__((address_space(3)))
; __device__ __forceinline__ unsigned cvt_pk_bf16(float lo, float hi) { unsigned r; asm volatile("v_cvt_pk_bf16_f32 %0, %1, %2" : "=v"(r) : "v"(lo), "v"(hi)); return r; }
; #define lane lane_id()
; __device__ __forceinline__ void conv_store4_lds(int K, int N, bf16_t* __restrict__ WT, int item, int lane, const float* __restrict__ gk, const f32x4 (&x)[16], PG8_LAS unsigned char* sw) {
;     const int nblk = N / 64, k0 = 64 * (item / nblk), n0 = 64 * (item % nblk);
;     const int nq = lane & 15, r = lane >> 4;
;     u32x4 o[8];
; #pragma unroll
;     for (int kc = 0; kc < 8; ++kc) {
;         float g[8];
; #pragma unroll
;         for (int j = 0; j < 8; ++j) g[j] = gk ? gk[k0 + 8 * kc + j] : 1.0f;
;         const f32x4 lo = x[2 * kc], hi = x[2 * kc + 1];
;         o[kc].x = cvt_pk_bf16(lo[0] * g[0], lo[1] * g[1]); o[kc].y = cvt_pk_bf16(lo[2] * g[2], lo[3] * g[3]);
;         o[kc].z = cvt_pk_bf16(hi[0] * g[4], hi[1] * g[5]); o[kc].w = cvt_pk_bf16(hi[2] * g[6], hi[3] * g[7]);
;     }
; #pragma unroll
;     for (int q = 0; q < 4; ++q) {
;         if ((nq >> 2) == q) {
;             PG8_LAS u32x4* wp = (PG8_LAS u32x4*)(sw + (4 * (nq & 3) + r) * 128);
; #pragma unroll
;             for (int kc = 0; kc < 8; ++kc) wp[kc] = o[kc];
;         }
;         asm volatile("s_waitcnt lgkmcnt(0)" ::: "memory");
; #pragma unroll
;         for (int h = 0; h < 2; ++h) { const int rl = (lane >> 3) + 8 * h;
;             const u32x4 v = *(const PG8_LAS u32x4*)(sw + rl * 128 + (lane & 7) * 16);
;             __builtin_nontemporal_store(v, (u32x4*)(WT + (size_t)(n0 + 16 * q + rl) * K + k0 + 8 * (lane & 7))); }
;         asm volatile("s_waitcnt lgkmcnt(0)" ::: "memory");
;     }
; }
;     __device__ __forceinline__ void done(const Unit&) const {
;     ...
;         for (int it = gw; it < I2; it += ngw) {
;             const bool two = it < I4;
;             conv_load4(w2, DM, it, ln, va); if (two) conv_load4(w4, DM, it, ln, vb);
;             conv_xpose(va, ln); if (two) conv_xpose(vb, ln);
;             conv_store4_lds(GW, DM, t2, it, ln, nullptr, va, sw); if (two) conv_store4_lds(DM, DM, t4, it, ln, nullptr, vb, sw);
	v_cvt_pk_bf16_f32 v215, v18, v19
	v_cvt_pk_bf16_f32 v216, v20, v21
	v_cvt_pk_bf16_f32 v217, v22, v23
	v_cvt_pk_bf16_f32 v218, v24, v25
	v_cvt_pk_bf16_f32 v219, v26, v27
	v_cvt_pk_bf16_f32 v220, v28, v29
	v_cvt_pk_bf16_f32 v221, v30, v31
	v_cvt_pk_bf16_f32 v222, v32, v33
	v_cvt_pk_bf16_f32 v223, v34, v35
	v_cvt_pk_bf16_f32 v224, v36, v37
	v_cvt_pk_bf16_f32 v225, v38, v39
	v_cvt_pk_bf16_f32 v226, v40, v41
	v_cvt_pk_bf16_f32 v227, v42, v43
	v_cvt_pk_bf16_f32 v228, v44, v45
	v_cvt_pk_bf16_f32 v229, v46, v47
	v_cvt_pk_bf16_f32 v230, v48, v49
	v_cvt_pk_bf16_f32 v231, v50, v51
	v_cvt_pk_bf16_f32 v232, v52, v53
	v_cvt_pk_bf16_f32 v233, v54, v55
	v_cvt_pk_bf16_f32 v234, v56, v57
	v_cvt_pk_bf16_f32 v235, v58, v59
	v_cvt_pk_bf16_f32 v236, v60, v61
	v_cvt_pk_bf16_f32 v237, v62, v63
	s_mov_b32 s37, s96
	s_lshr_b32 s18, s37, 5
	s_lshl_b32 s18, s18, 6
	s_and_b32 s19, s37, 31
	s_lshl_b32 s19, s19, 6
	s_lshl_b32 s49, s19, 13
	s_lshl_b32 s50, s18, 1
	s_add_i32 s39, s49, s50
	v_add_u32_e32 v240, s18, v153
	v_mov_b32_e32 v241, 0
	v_lshlrev_b64 v[240:241], 13, v[240:241]
	s_lshl_b32 s100, s19, 2
	s_mov_b32 s101, 0
	v_lshl_add_u64 v[238:239], s[100:101], 0, v[140:141]
	v_lshl_add_u64 v[238:239], v[238:239], 0, v[240:241]
	s_mov_b32 s46, 0x8000
	s_mov_b32 s47, 0
	global_load_dwordx4 v[0:3], v[238:239], off nt
	v_lshl_add_u64 v[238:239], v[238:239], 0, s[46:47]
	global_load_dwordx4 v[4:7], v[238:239], off nt
	v_lshl_add_u64 v[238:239], v[238:239], 0, s[46:47]
	global_load_dwordx4 v[8:11], v[238:239], off nt
	v_lshl_add_u64 v[238:239], v[238:239], 0, s[46:47]
	global_load_dwordx4 v[12:15], v[238:239], off nt
	v_lshl_add_u64 v[238:239], v[238:239], 0, s[46:47]
	global_load_dwordx4 v[16:19], v[238:239], off nt
	v_lshl_add_u64 v[238:239], v[238:239], 0, s[46:47]
	global_load_dwordx4 v[20:23], v[238:239], off nt
	v_lshl_add_u64 v[238:239], v[238:239], 0, s[46:47]
	global_load_dwordx4 v[24:27], v[238:239], off nt
	v_lshl_add_u64 v[238:239], v[238:239], 0, s[46:47]
	global_load_dwordx4 v[28:31], v[238:239], off nt
	v_lshl_add_u64 v[238:239], v[238:239], 0, s[46:47]
	global_load_dwordx4 v[32:35], v[238:239], off nt
	v_lshl_add_u64 v[238:239], v[238:239], 0, s[46:47]
	global_load_dwordx4 v[36:39], v[238:239], off nt
	v_lshl_add_u64 v[238:239], v[238:239], 0, s[46:47]
	global_load_dwordx4 v[40:43], v[238:239], off nt
	v_lshl_add_u64 v[238:239], v[238:239], 0, s[46:47]
	global_load_dwordx4 v[44:47], v[238:239], off nt
	v_lshl_add_u64 v[238:239], v[238:239], 0, s[46:47]
	global_load_dwordx4 v[48:51], v[238:239], off nt
	v_lshl_add_u64 v[238:239], v[238:239], 0, s[46:47]
	global_load_dwordx4 v[52:55], v[238:239], off nt
	v_lshl_add_u64 v[238:239], v[238:239], 0, s[46:47]
	global_load_dwordx4 v[56:59], v[238:239], off nt
	v_lshl_add_u64 v[238:239], v[238:239], 0, s[46:47]
	global_load_dwordx4 v[60:63], v[238:239], off nt
	s_mov_b32 s44, s24
	s_mov_b32 s45, 0
	s_mov_b32 s100, 0x8000
	s_mov_b32 s101, 0
	v_lshlrev_b32_e32 v170, 12, v197
	v_mov_b32_e32 v171, 0
	s_and_saveexec_b64 s[22:23], s[8:9]
	ds_write_b128 v196, v[206:209]
	ds_write_b128 v196, v[210:213] offset:16
	ds_write_b128 v196, v[214:217] offset:32
	ds_write_b128 v196, v[218:221] offset:48
	ds_write_b128 v196, v[222:225] offset:64
	ds_write_b128 v196, v[226:229] offset:80
	ds_write_b128 v196, v[230:233] offset:96
	ds_write_b128 v196, v[234:237] offset:112
	s_mov_b64 exec, s[22:23]
	s_waitcnt lgkmcnt(0)
	ds_read_b128 v[158:161], v246
	ds_read_b128 v[162:165], v247
	v_lshl_add_u64 v[166:167], s[44:45], 0, v[138:139]
	v_lshl_add_u64 v[166:167], v[166:167], 0, v[170:171]
	v_lshl_add_u64 v[168:169], v[166:167], 0, s[100:101]
	s_waitcnt lgkmcnt(0)
	global_store_dwordx4 v[166:167], v[158:161], off nt
	global_store_dwordx4 v[168:169], v[162:165], off nt
	s_add_u32 s44, s44, 0x10000
	s_and_saveexec_b64 s[22:23], s[10:11]
	ds_write_b128 v196, v[206:209]
	ds_write_b128 v196, v[210:213] offset:16
	ds_write_b128 v196, v[214:217] offset:32
	ds_write_b128 v196, v[218:221] offset:48
	ds_write_b128 v196, v[222:225] offset:64
	ds_write_b128 v196, v[226:229] offset:80
	ds_write_b128 v196, v[230:233] offset:96
	ds_write_b128 v196, v[234:237] offset:112
	s_mov_b64 exec, s[22:23]
	s_waitcnt lgkmcnt(0)
	ds_read_b128 v[238:241], v246
	ds_read_b128 v[242:245], v247
	v_lshl_add_u64 v[166:167], s[44:45], 0, v[138:139]
	v_lshl_add_u64 v[166:167], v[166:167], 0, v[170:171]
	v_lshl_add_u64 v[168:169], v[166:167], 0, s[100:101]
	s_waitcnt lgkmcnt(0)
	global_store_dwordx4 v[166:167], v[238:241], off nt
	global_store_dwordx4 v[168:169], v[242:245], off nt
	s_add_u32 s44, s44, 0x10000
	s_and_saveexec_b64 s[22:23], s[12:13]
	ds_write_b128 v196, v[206:209]
	ds_write_b128 v196, v[210:213] offset:16
	ds_write_b128 v196, v[214:217] offset:32
	ds_write_b128 v196, v[218:221] offset:48
	ds_write_b128 v196, v[222:225] offset:64
	ds_write_b128 v196, v[226:229] offset:80
	ds_write_b128 v196, v[230:233] offset:96
	ds_write_b128 v196, v[234:237] offset:112
	s_mov_b64 exec, s[22:23]
	s_waitcnt lgkmcnt(0)
	ds_read_b128 v[158:161], v246
	ds_read_b128 v[162:165], v247
	v_lshl_add_u64 v[166:167], s[44:45], 0, v[138:139]
	v_lshl_add_u64 v[166:167], v[166:167], 0, v[170:171]
	v_lshl_add_u64 v[168:169], v[166:167], 0, s[100:101]
	s_waitcnt lgkmcnt(0)
	global_store_dwordx4 v[166:167], v[158:161], off nt
	global_store_dwordx4 v[168:169], v[162:165], off nt
	s_add_u32 s44, s44, 0x10000
	s_and_saveexec_b64 s[22:23], s[14:15]
	ds_write_b128 v196, v[206:209]
	ds_write_b128 v196, v[210:213] offset:16
	ds_write_b128 v196, v[214:217] offset:32
	ds_write_b128 v196, v[218:221] offset:48
	ds_write_b128 v196, v[222:225] offset:64
	ds_write_b128 v196, v[226:229] offset:80
	ds_write_b128 v196, v[230:233] offset:96
	ds_write_b128 v196, v[234:237] offset:112
	s_mov_b64 exec, s[22:23]
	s_waitcnt lgkmcnt(0)
; #define PG8_LAS __attribute__((address_space(3)))
; __device__ __forceinline__ unsigned cvt_pk_bf16(float lo, float hi) { unsigned r; asm volatile("v_cvt_pk_bf16_f32 %0, %1, %2" : "=v"(r) : "v"(lo), "v"(hi)); return r; }
; #define lane lane_id()
; __device__ __forceinline__ void conv_store4_lds(int K, int N, bf16_t* __restrict__ WT, int item, int lane, const float* __restrict__ gk, const f32x4 (&x)[16], PG8_LAS unsigned char* sw) {
;     const int nblk = N / 64, k0 = 64 * (item / nblk), n0 = 64 * (item % nblk);
;     const int nq = lane & 15, r = lane >> 4;
;     u32x4 o[8];
; #pragma unroll
;     for (int kc = 0; kc < 8; ++kc) {
;         float g[8];
; #pragma unroll
;         for (int j = 0; j < 8; ++j) g[j] = gk ? gk[k0 + 8 * kc + j] : 1.0f;
;         const f32x4 lo = x[2 * kc], hi = x[2 * kc + 1];
;         o[kc].x = cvt_pk_bf16(lo[0] * g[0], lo[1] * g[1]); o[kc].y = cvt_pk_bf16(lo[2] * g[2], lo[3] * g[3]);
;         o[kc].z = cvt_pk_bf16(hi[0] * g[4], hi[1] * g[5]); o[kc].w = cvt_pk_bf16(hi[2] * g[6], hi[3] * g[7]);
;     }
; #pragma unroll
;     for (int q = 0; q < 4; ++q) {
;         if ((nq >> 2) == q) {
;             PG8_LAS u32x4* wp = (PG8_LAS u32x4*)(sw + (4 * (nq & 3) + r) * 128);
; #pragma unroll
;             for (int kc = 0; kc < 8; ++kc) wp[kc] = o[kc];
;         }
;         asm volatile("s_waitcnt lgkmcnt(0)" ::: "memory");
; #pragma unroll
;         for (int h = 0; h < 2; ++h) { const int rl = (lane >> 3) + 8 * h;
;             const u32x4 v = *(const PG8_LAS u32x4*)(sw + rl * 128 + (lane & 7) * 16);
;             __builtin_nontemporal_store(v, (u32x4*)(WT + (size_t)(n0 + 16 * q + rl) * K + k0 + 8 * (lane & 7))); }
;         asm volatile("s_waitcnt lgkmcnt(0)" ::: "memory");
;     }
; }
	ds_read_b128 v[238:241], v246
	ds_read_b128 v[242:245], v247
	v_lshl_add_u64 v[166:167], s[44:45], 0, v[138:139]
	v_lshl_add_u64 v[166:167], v[166:167], 0, v[170:171]
	v_lshl_add_u64 v[168:169], v[166:167], 0, s[100:101]
	s_waitcnt lgkmcnt(0)
	global_store_dwordx4 v[166:167], v[238:241], off nt
	global_store_dwordx4 v[168:169], v[242:245], off nt
	s_waitcnt vmcnt(24)
	v_pk_mul_f32 v[64:65], v[64:65], v[174:175] op_sel_hi:[1,0]
	v_pk_mul_f32 v[66:67], v[66:67], v[174:175] op_sel_hi:[1,0]
	v_pk_mul_f32 v[68:69], v[68:69], v[174:175] op_sel:[0,1] op_sel_hi:[1,1]
	v_pk_mul_f32 v[70:71], v[70:71], v[174:175] op_sel:[0,1] op_sel_hi:[1,1]
	v_pk_mul_f32 v[72:73], v[72:73], v[176:177] op_sel_hi:[1,0]
	v_pk_mul_f32 v[74:75], v[74:75], v[176:177] op_sel_hi:[1,0]
	v_pk_mul_f32 v[76:77], v[76:77], v[176:177] op_sel:[0,1] op_sel_hi:[1,1]
	v_pk_mul_f32 v[78:79], v[78:79], v[176:177] op_sel:[0,1] op_sel_hi:[1,1]
	v_pk_mul_f32 v[80:81], v[80:81], v[178:179] op_sel_hi:[1,0]
	v_pk_mul_f32 v[82:83], v[82:83], v[178:179] op_sel_hi:[1,0]
	v_pk_mul_f32 v[84:85], v[84:85], v[178:179] op_sel:[0,1] op_sel_hi:[1,1]
	v_pk_mul_f32 v[86:87], v[86:87], v[178:179] op_sel:[0,1] op_sel_hi:[1,1]
	v_pk_mul_f32 v[88:89], v[88:89], v[180:181] op_sel_hi:[1,0]
	v_pk_mul_f32 v[90:91], v[90:91], v[180:181] op_sel_hi:[1,0]
	v_pk_mul_f32 v[92:93], v[92:93], v[180:181] op_sel:[0,1] op_sel_hi:[1,1]
	v_pk_mul_f32 v[94:95], v[94:95], v[180:181] op_sel:[0,1] op_sel_hi:[1,1]
	v_pk_mul_f32 v[96:97], v[96:97], v[182:183] op_sel_hi:[1,0]
	v_pk_mul_f32 v[98:99], v[98:99], v[182:183] op_sel_hi:[1,0]
	v_pk_mul_f32 v[100:101], v[100:101], v[182:183] op_sel:[0,1] op_sel_hi:[1,1]
	v_pk_mul_f32 v[102:103], v[102:103], v[182:183] op_sel:[0,1] op_sel_hi:[1,1]
	v_pk_mul_f32 v[104:105], v[104:105], v[184:185] op_sel_hi:[1,0]
	v_pk_mul_f32 v[106:107], v[106:107], v[184:185] op_sel_hi:[1,0]
	v_pk_mul_f32 v[108:109], v[108:109], v[184:185] op_sel:[0,1] op_sel_hi:[1,1]
	v_pk_mul_f32 v[110:111], v[110:111], v[184:185] op_sel:[0,1] op_sel_hi:[1,1]
	v_pk_mul_f32 v[112:113], v[112:113], v[186:187] op_sel_hi:[1,0]
	v_pk_mul_f32 v[114:115], v[114:115], v[186:187] op_sel_hi:[1,0]
	v_pk_mul_f32 v[116:117], v[116:117], v[186:187] op_sel:[0,1] op_sel_hi:[1,1]
	v_pk_mul_f32 v[118:119], v[118:119], v[186:187] op_sel:[0,1] op_sel_hi:[1,1]
	v_pk_mul_f32 v[120:121], v[120:121], v[188:189] op_sel_hi:[1,0]
	v_pk_mul_f32 v[122:123], v[122:123], v[188:189] op_sel_hi:[1,0]
	v_pk_mul_f32 v[124:125], v[124:125], v[188:189] op_sel:[0,1] op_sel_hi:[1,1]
	v_pk_mul_f32 v[126:127], v[126:127], v[188:189] op_sel:[0,1] op_sel_hi:[1,1]
	v_permlane16_swap_b32_e32 v64, v65
	v_permlane16_swap_b32_e32 v66, v67
	v_permlane16_swap_b32_e32 v68, v69
	v_permlane16_swap_b32_e32 v70, v71
	v_permlane16_swap_b32_e32 v72, v73
	v_permlane16_swap_b32_e32 v74, v75
	v_permlane16_swap_b32_e32 v76, v77
	v_permlane16_swap_b32_e32 v78, v79
	v_permlane16_swap_b32_e32 v80, v81
	v_permlane16_swap_b32_e32 v82, v83
	v_permlane16_swap_b32_e32 v84, v85
	v_permlane16_swap_b32_e32 v86, v87
	v_permlane16_swap_b32_e32 v88, v89
	v_permlane16_swap_b32_e32 v90, v91
	v_permlane16_swap_b32_e32 v92, v93
	v_permlane16_swap_b32_e32 v94, v95
	v_permlane16_swap_b32_e32 v96, v97
	v_permlane16_swap_b32_e32 v98, v99
	v_permlane16_swap_b32_e32 v100, v101
	v_permlane16_swap_b32_e32 v102, v103
	v_permlane16_swap_b32_e32 v104, v105
	v_permlane16_swap_b32_e32 v106, v107
	v_permlane16_swap_b32_e32 v108, v109
	v_permlane16_swap_b32_e32 v110, v111
	v_permlane16_swap_b32_e32 v112, v113
	v_permlane16_swap_b32_e32 v114, v115
	v_permlane16_swap_b32_e32 v116, v117
	v_permlane16_swap_b32_e32 v118, v119
	v_permlane16_swap_b32_e32 v120, v121
	v_permlane16_swap_b32_e32 v122, v123
	v_permlane16_swap_b32_e32 v124, v125
	v_permlane16_swap_b32_e32 v126, v127
	v_permlane32_swap_b32_e32 v64, v66
	v_permlane32_swap_b32_e32 v65, v67
	v_permlane32_swap_b32_e32 v68, v70
	v_permlane32_swap_b32_e32 v69, v71
	v_permlane32_swap_b32_e32 v72, v74
	v_permlane32_swap_b32_e32 v73, v75
	v_permlane32_swap_b32_e32 v76, v78
	v_permlane32_swap_b32_e32 v77, v79
	v_permlane32_swap_b32_e32 v80, v82
	v_permlane32_swap_b32_e32 v81, v83
	v_permlane32_swap_b32_e32 v84, v86
	v_permlane32_swap_b32_e32 v85, v87
	v_permlane32_swap_b32_e32 v88, v90
	v_permlane32_swap_b32_e32 v89, v91
	v_permlane32_swap_b32_e32 v92, v94
	v_permlane32_swap_b32_e32 v93, v95
	v_permlane32_swap_b32_e32 v96, v98
	v_permlane32_swap_b32_e32 v97, v99
	v_permlane32_swap_b32_e32 v100, v102
	v_permlane32_swap_b32_e32 v101, v103
	v_permlane32_swap_b32_e32 v104, v106
	v_permlane32_swap_b32_e32 v105, v107
	v_permlane32_swap_b32_e32 v108, v110
	v_permlane32_swap_b32_e32 v109, v111
	v_permlane32_swap_b32_e32 v112, v114
	v_permlane32_swap_b32_e32 v113, v115
	v_permlane32_swap_b32_e32 v116, v118
	v_permlane32_swap_b32_e32 v117, v119
	v_permlane32_swap_b32_e32 v120, v122
	v_permlane32_swap_b32_e32 v121, v123
	v_permlane32_swap_b32_e32 v124, v126
	v_permlane32_swap_b32_e32 v125, v127
	v_cvt_pk_bf16_f32 v206, v64, v65
	v_cvt_pk_bf16_f32 v207, v66, v67
	v_cvt_pk_bf16_f32 v208, v68, v69
	v_cvt_pk_bf16_f32 v209, v70, v71
	v_cvt_pk_bf16_f32 v210, v72, v73
	v_cvt_pk_bf16_f32 v211, v74, v75
	v_cvt_pk_bf16_f32 v212, v76, v77
	v_cvt_pk_bf16_f32 v213, v78, v79
	v_cvt_pk_bf16_f32 v214, v80, v81
	v_cvt_pk_bf16_f32 v215, v82, v83
	v_cvt_pk_bf16_f32 v216, v84, v85
	v_cvt_pk_bf16_f32 v217, v86, v87
	v_cvt_pk_bf16_f32 v218, v88, v89
	v_cvt_pk_bf16_f32 v219, v90, v91
	v_cvt_pk_bf16_f32 v220, v92, v93
	v_cvt_pk_bf16_f32 v221, v94, v95
	v_cvt_pk_bf16_f32 v222, v96, v97
	v_cvt_pk_bf16_f32 v223, v98, v99
	v_cvt_pk_bf16_f32 v224, v100, v101
	v_cvt_pk_bf16_f32 v225, v102, v103
	v_cvt_pk_bf16_f32 v226, v104, v105
	v_cvt_pk_bf16_f32 v227, v106, v107
	v_cvt_pk_bf16_f32 v228, v108, v109
	v_cvt_pk_bf16_f32 v229, v110, v111
	v_cvt_pk_bf16_f32 v230, v112, v113
	v_cvt_pk_bf16_f32 v231, v114, v115
	v_cvt_pk_bf16_f32 v232, v116, v117
	v_cvt_pk_bf16_f32 v233, v118, v119
	v_cvt_pk_bf16_f32 v234, v120, v121
	v_cvt_pk_bf16_f32 v235, v122, v123
	v_cvt_pk_bf16_f32 v236, v124, v125
	v_cvt_pk_bf16_f32 v237, v126, v127
	s_cmpk_lt_u32 s96, 0x400
	s_cbranch_scc0 .Lhk_noD1
; #define lane lane_id()
; __device__ __forceinline__ void conv_load4(const float* __restrict__ W, int N, int item, int lane, f32x4 (&x)[16]) {
;     const int nblk = N / 64, k0 = 64 * (item / nblk), n0 = 64 * (item % nblk);
; #pragma unroll
;     for (int i = 0; i < 16; ++i) x[i] = __builtin_nontemporal_load((const f32x4*)(W + (size_t)(k0 + 4 * i + (lane >> 4)) * N + n0 + 4 * (lane & 15)));
; }
;     __device__ __forceinline__ void done(const Unit&) const {
;     ...
;         for (int it = gw; it < I2; it += ngw) {
;             const bool two = it < I4;
;             conv_load4(w2, DM, it, ln, va); if (two) conv_load4(w4, DM, it, ln, vb);
	s_mov_b32 s37, s96
	s_lshr_b32 s18, s37, 5
	s_lshl_b32 s18, s18, 6
	s_and_b32 s19, s37, 31
	s_lshl_b32 s19, s19, 6
	s_lshl_b32 s49, s19, 12
	s_lshl_b32 s50, s18, 1
	s_add_i32 s48, s49, s50
	v_add_u32_e32 v240, s18, v153
	v_mov_b32_e32 v241, 0
	v_lshlrev_b64 v[240:241], 13, v[240:241]
	s_lshl_b32 s100, s19, 2
	s_mov_b32 s101, 0
	v_lshl_add_u64 v[238:239], s[100:101], 0, v[142:143]
	v_lshl_add_u64 v[238:239], v[238:239], 0, v[240:241]
	s_mov_b32 s46, 0x8000
	s_mov_b32 s47, 0
	global_load_dwordx4 v[64:67], v[238:239], off nt
	v_lshl_add_u64 v[238:239], v[238:239], 0, s[46:47]
	global_load_dwordx4 v[68:71], v[238:239], off nt
	v_lshl_add_u64 v[238:239], v[238:239], 0, s[46:47]
	global_load_dwordx4 v[72:75], v[238:239], off nt
	v_lshl_add_u64 v[238:239], v[238:239], 0, s[46:47]
	global_load_dwordx4 v[76:79], v[238:239], off nt
	v_lshl_add_u64 v[238:239], v[238:239], 0, s[46:47]
	global_load_dwordx4 v[80:83], v[238:239], off nt
	v_lshl_add_u64 v[238:239], v[238:239], 0, s[46:47]
	global_load_dwordx4 v[84:87], v[238:239], off nt
	v_lshl_add_u64 v[238:239], v[238:239], 0, s[46:47]
	global_load_dwordx4 v[88:91], v[238:239], off nt
	v_lshl_add_u64 v[238:239], v[238:239], 0, s[46:47]
	global_load_dwordx4 v[92:95], v[238:239], off nt
	v_lshl_add_u64 v[238:239], v[238:239], 0, s[46:47]
	global_load_dwordx4 v[96:99], v[238:239], off nt
	v_lshl_add_u64 v[238:239], v[238:239], 0, s[46:47]
	global_load_dwordx4 v[100:103], v[238:239], off nt
	v_lshl_add_u64 v[238:239], v[238:239], 0, s[46:47]
	global_load_dwordx4 v[104:107], v[238:239], off nt
	v_lshl_add_u64 v[238:239], v[238:239], 0, s[46:47]
	global_load_dwordx4 v[108:111], v[238:239], off nt
	v_lshl_add_u64 v[238:239], v[238:239], 0, s[46:47]
	global_load_dwordx4 v[112:115], v[238:239], off nt
	v_lshl_add_u64 v[238:239], v[238:239], 0, s[46:47]
	global_load_dwordx4 v[116:119], v[238:239], off nt
	v_lshl_add_u64 v[238:239], v[238:239], 0, s[46:47]
	global_load_dwordx4 v[120:123], v[238:239], off nt
	v_lshl_add_u64 v[238:239], v[238:239], 0, s[46:47]
	global_load_dwordx4 v[124:127], v[238:239], off nt

;     __device__ __forceinline__ void done(const Unit&) const {
;         constexpr int I2 = (GW / 64) * (DM / 64), I3 = (DM / 64) * (4 * DM / 64), I4 = (DM / 64) * (DM / 64);
;         const int u = n_done++;
;     ...
;         f32x4 va[16];
;         if (u == 0 || u == 1) { for (int it = gw + u * ngw; it < I3; it += 2 * ngw) { conv_load4(w3, 4 * DM, it, ln, va); conv_xpose(va, ln); conv_store4(DM, 4 * DM, t3, it, ln, g1, va); } }
;         else if (u == 2) { for (int it = gw; it < I2; it += ngw) { conv_load4(w2, DM, it, ln, va); conv_xpose(va, ln); conv_store4(GW, DM, t2, it, ln, nullptr, va); } }
;         else if (u == 3) { for (int it = gw; it < I4; it += ngw) { conv_load4(w4, DM, it, ln, va); conv_xpose(va, ln); conv_store4(DM, DM, t4, it, ln, nullptr, va); } }
;     ...
;         if (u != trigger) return;
;         f32x4 va[16], vb[16];
;         for (int it = gw; it < I3; it += 2 * ngw) {
;             const bool two = it + ngw < I3;
;             conv_load4(w3, 4 * DM, it, ln, va); if (two) conv_load4(w3, 4 * DM, it + ngw, ln, vb);
;             conv_xpose(va, ln); if (two) conv_xpose(vb, ln);
;             conv_store4_lds(DM, 4 * DM, t3, it, ln, g1, va, sw); if (two) conv_store4_lds(DM, 4 * DM, t3, it + ngw, ln, g1, vb, sw);
;         }
;         for (int it = gw; it < I2; it += ngw) {
;             const bool two = it < I4;
;             conv_load4(w2, DM, it, ln, va); if (two) conv_load4(w4, DM, it, ln, vb);
;             conv_xpose(va, ln); if (two) conv_xpose(vb, ln);
;             conv_store4_lds(GW, DM, t2, it, ln, nullptr, va, sw); if (two) conv_store4_lds(DM, DM, t4, it, ln, nullptr, vb, sw);
;         }
;     ...
;     }
.Lhk_end:
	s_branch .LBB0_203
